# v38 plus W_in projection epilogue: row-norm loads batched, no per-row drains
# baseline (speedup 1.0000x reference)
; __device__ __forceinline__ unsigned cvt_pk_bf16(float lo, float hi) { const f32x2 v = {lo, hi}; return __builtin_bit_cast(unsigned, __builtin_convertvector(v, bf16x2_t)); }
;     __device__ __forceinline__ void operator()(const f32x4 (&acc)[2][2][4][2], const Unit& u, int wr, int wc, int fr_, int fq_) const {
;     ...
;             const int row0 = u.pm * 256 + wr * 64 + fr;
;             if (u.pn < 8) {
;     ...
;                 const int col0 = (u.pn - 8) * 256 + wc * 32 + 8 * fq;
; #pragma unroll
;                 for (int ai = 0; ai < 2; ++ai)
; #pragma unroll
;                     for (int m = 0; m < 4; ++m) {
;                         const int row = row0 + ai * 128 + m * 16;
;                         const float rs = rsqrtf(ssq[row] * (1.0f / DM) + 1e-6f);
; #pragma unroll
;                         for (int bj = 0; bj < 2; ++bj) {
;                             const f32x4 v0 = acc[ai][bj][m][0] * rs, v1 = acc[ai][bj][m][1] * rs;
;                             u32x4 w; w.x = cvt_pk_bf16(v0[0], v0[1]); w.y = cvt_pk_bf16(v0[2], v0[3]); w.z = cvt_pk_bf16(v1[0], v1[1]); w.w = cvt_pk_bf16(v1[2], v1[3]);
;                             *(u32x4*)(P + (size_t)row * PROJ_LD + col0 + bj * 128) = w;
;                         }
;                     }
.LBB0_736:
	s_lshl_b32 s1, s13, 8
	s_add_i32 s1, s1, s80
	v_add_u32_e32 v156, s1, v186
	s_cmp_gt_i32 s0, 7
	s_mov_b64 s[6:7], -1
	s_cbranch_scc0 .LBB0_742
	s_and_b32 s1, s0, 0x7ffffffe
	s_cmp_lg_u32 s1, 18
	s_cbranch_scc0 .LBB0_739
	v_ashrrev_i32_e32 v157, 31, v156
	v_lshl_add_u64 v[0:1], v[156:157], 2, s[18:19]
	global_load_dword v240, v[0:1], off
	global_load_dword v241, v[0:1], off offset:64
	global_load_dword v242, v[0:1], off offset:128
	global_load_dword v243, v[0:1], off offset:192
	global_load_dword v244, v[0:1], off offset:512
	global_load_dword v245, v[0:1], off offset:576
	global_load_dword v246, v[0:1], off offset:640
	global_load_dword v247, v[0:1], off offset:704
	s_lshl_b32 s1, s0, 8
	s_add_i32 s1, s50, s1
	v_lshl_add_u32 v2, v232, 3, s1
	v_ashrrev_i32_e32 v3, 31, v2
	v_lshl_add_u64 v[2:3], v[2:3], 1, s[26:27]
	v_mad_i64_i32 v[12:13], s[6:7], v156, s95, v[2:3]
	s_waitcnt vmcnt(0)
	v_mov_b32_e32 v4, v240
	v_fmamk_f32 v4, v4, 0x3a000000, v230
	v_mul_f32_e32 v5, 0x4b800000, v4
	v_cmp_gt_f32_e32 vcc, s94, v4
	s_nop 1
	v_cndmask_b32_e32 v4, v4, v5, vcc
	v_rsq_f32_e32 v4, v4
	s_nop 0
	v_mul_f32_e32 v5, 0x45800000, v4
	v_cndmask_b32_e32 v4, v4, v5, vcc
	v_pk_mul_f32 v[6:7], v[150:151], v[4:5] op_sel_hi:[1,0]
	v_pk_mul_f32 v[8:9], v[148:149], v[4:5] op_sel_hi:[1,0]
	v_pk_mul_f32 v[10:11], v[146:147], v[4:5] op_sel_hi:[1,0]
	v_pk_mul_f32 v[14:15], v[144:145], v[4:5] op_sel_hi:[1,0]
	v_pk_mul_f32 v[16:17], v[142:143], v[4:5] op_sel_hi:[1,0]
	v_pk_mul_f32 v[18:19], v[140:141], v[4:5] op_sel_hi:[1,0]
	v_pk_mul_f32 v[20:21], v[138:139], v[4:5] op_sel_hi:[1,0]
	v_pk_mul_f32 v[22:23], v[136:137], v[4:5] op_sel_hi:[1,0]
	v_cvt_pk_bf16_f32 v4, v8, v9
	v_cvt_pk_bf16_f32 v5, v6, v7
	v_cvt_pk_bf16_f32 v6, v14, v15
	v_cvt_pk_bf16_f32 v7, v10, v11
	v_cvt_pk_bf16_f32 v8, v18, v19
	v_cvt_pk_bf16_f32 v9, v16, v17
	v_cvt_pk_bf16_f32 v10, v22, v23
	v_cvt_pk_bf16_f32 v11, v20, v21
	global_store_dwordx4 v[12:13], v[4:7], off
	global_store_dwordx4 v[12:13], v[8:11], off offset:256
	global_load_dword v248, v[0:1], off
	s_nop 1
	v_mov_b32_e32 v4, v241
	v_fmamk_f32 v4, v4, 0x3a000000, v230
	v_mul_f32_e32 v5, 0x4b800000, v4
	v_cmp_gt_f32_e32 vcc, s94, v4
	s_nop 1
	v_cndmask_b32_e32 v4, v4, v5, vcc
	v_rsq_f32_e32 v4, v4
	v_add_u32_e32 v5, 16, v156
	v_mad_i64_i32 v[12:13], s[6:7], v5, s95, v[2:3]
	v_mul_f32_e32 v5, 0x45800000, v4
	v_cndmask_b32_e32 v4, v4, v5, vcc
	v_pk_mul_f32 v[6:7], v[134:135], v[4:5] op_sel_hi:[1,0]
	v_pk_mul_f32 v[8:9], v[132:133], v[4:5] op_sel_hi:[1,0]
	v_pk_mul_f32 v[10:11], v[130:131], v[4:5] op_sel_hi:[1,0]
	v_pk_mul_f32 v[14:15], v[128:129], v[4:5] op_sel_hi:[1,0]
	v_pk_mul_f32 v[16:17], v[126:127], v[4:5] op_sel_hi:[1,0]
	v_pk_mul_f32 v[18:19], v[124:125], v[4:5] op_sel_hi:[1,0]
	v_pk_mul_f32 v[20:21], v[122:123], v[4:5] op_sel_hi:[1,0]
	v_pk_mul_f32 v[22:23], v[120:121], v[4:5] op_sel_hi:[1,0]
	v_cvt_pk_bf16_f32 v4, v8, v9
	v_cvt_pk_bf16_f32 v5, v6, v7
	v_cvt_pk_bf16_f32 v6, v14, v15
	v_cvt_pk_bf16_f32 v7, v10, v11
	v_cvt_pk_bf16_f32 v8, v18, v19
	v_cvt_pk_bf16_f32 v9, v16, v17
	v_cvt_pk_bf16_f32 v10, v22, v23
	v_cvt_pk_bf16_f32 v11, v20, v21
	global_store_dwordx4 v[12:13], v[4:7], off
	global_store_dwordx4 v[12:13], v[8:11], off offset:256
	global_load_dword v248, v[0:1], off
	s_nop 1
	v_mov_b32_e32 v4, v242
	v_fmamk_f32 v4, v4, 0x3a000000, v230
	v_mul_f32_e32 v5, 0x4b800000, v4
	v_cmp_gt_f32_e32 vcc, s94, v4
	s_nop 1
	v_cndmask_b32_e32 v4, v4, v5, vcc
	v_rsq_f32_e32 v4, v4
	v_add_u32_e32 v5, 32, v156
	v_mad_i64_i32 v[12:13], s[6:7], v5, s95, v[2:3]
	v_mul_f32_e32 v5, 0x45800000, v4
	v_cndmask_b32_e32 v4, v4, v5, vcc
	v_pk_mul_f32 v[6:7], v[118:119], v[4:5] op_sel_hi:[1,0]
	v_pk_mul_f32 v[8:9], v[116:117], v[4:5] op_sel_hi:[1,0]
	v_pk_mul_f32 v[10:11], v[114:115], v[4:5] op_sel_hi:[1,0]
	v_pk_mul_f32 v[14:15], v[112:113], v[4:5] op_sel_hi:[1,0]
	v_pk_mul_f32 v[16:17], v[110:111], v[4:5] op_sel_hi:[1,0]
	v_pk_mul_f32 v[18:19], v[108:109], v[4:5] op_sel_hi:[1,0]
	v_pk_mul_f32 v[20:21], v[106:107], v[4:5] op_sel_hi:[1,0]
	v_pk_mul_f32 v[22:23], v[104:105], v[4:5] op_sel_hi:[1,0]
	v_cvt_pk_bf16_f32 v4, v8, v9
	v_cvt_pk_bf16_f32 v5, v6, v7
	v_cvt_pk_bf16_f32 v6, v14, v15
	v_cvt_pk_bf16_f32 v7, v10, v11
	v_cvt_pk_bf16_f32 v8, v18, v19
	v_cvt_pk_bf16_f32 v9, v16, v17
	v_cvt_pk_bf16_f32 v10, v22, v23
	v_cvt_pk_bf16_f32 v11, v20, v21
	global_store_dwordx4 v[12:13], v[4:7], off
	global_store_dwordx4 v[12:13], v[8:11], off offset:256
	global_load_dword v248, v[0:1], off
	s_nop 1
	v_mov_b32_e32 v4, v243
	v_fmamk_f32 v4, v4, 0x3a000000, v230
	v_mul_f32_e32 v5, 0x4b800000, v4
	v_cmp_gt_f32_e32 vcc, s94, v4
	s_nop 1
	v_cndmask_b32_e32 v4, v4, v5, vcc
	v_rsq_f32_e32 v4, v4
	v_add_u32_e32 v5, 48, v156
	v_mad_i64_i32 v[12:13], s[6:7], v5, s95, v[2:3]
	v_mul_f32_e32 v5, 0x45800000, v4
	v_cndmask_b32_e32 v4, v4, v5, vcc
	v_pk_mul_f32 v[6:7], v[102:103], v[4:5] op_sel_hi:[1,0]
	v_pk_mul_f32 v[8:9], v[100:101], v[4:5] op_sel_hi:[1,0]
	v_pk_mul_f32 v[10:11], v[98:99], v[4:5] op_sel_hi:[1,0]
	v_pk_mul_f32 v[14:15], v[96:97], v[4:5] op_sel_hi:[1,0]
	v_pk_mul_f32 v[16:17], v[94:95], v[4:5] op_sel_hi:[1,0]
	v_pk_mul_f32 v[18:19], v[92:93], v[4:5] op_sel_hi:[1,0]
	v_pk_mul_f32 v[20:21], v[90:91], v[4:5] op_sel_hi:[1,0]
	v_pk_mul_f32 v[22:23], v[88:89], v[4:5] op_sel_hi:[1,0]
	v_cvt_pk_bf16_f32 v4, v8, v9
	v_cvt_pk_bf16_f32 v5, v6, v7
	v_cvt_pk_bf16_f32 v6, v14, v15
	v_cvt_pk_bf16_f32 v7, v10, v11
	v_cvt_pk_bf16_f32 v8, v18, v19
	v_cvt_pk_bf16_f32 v9, v16, v17
	v_cvt_pk_bf16_f32 v10, v22, v23
	v_cvt_pk_bf16_f32 v11, v20, v21
	global_store_dwordx4 v[12:13], v[4:7], off
	global_store_dwordx4 v[12:13], v[8:11], off offset:256
	global_load_dword v248, v[0:1], off
; __device__ __forceinline__ unsigned cvt_pk_bf16(float lo, float hi) { const f32x2 v = {lo, hi}; return __builtin_bit_cast(unsigned, __builtin_convertvector(v, bf16x2_t)); }
;     __device__ __forceinline__ void operator()(const f32x4 (&acc)[2][2][4][2], const Unit& u, int wr, int wc, int fr_, int fq_) const {
;     ...
;                 const int col0 = (u.pn - 8) * 256 + wc * 32 + 8 * fq;
; #pragma unroll
;                 for (int ai = 0; ai < 2; ++ai)
; #pragma unroll
;                     for (int m = 0; m < 4; ++m) {
;                         const int row = row0 + ai * 128 + m * 16;
;                         const float rs = rsqrtf(ssq[row] * (1.0f / DM) + 1e-6f);
; #pragma unroll
;                         for (int bj = 0; bj < 2; ++bj) {
;                             const f32x4 v0 = acc[ai][bj][m][0] * rs, v1 = acc[ai][bj][m][1] * rs;
;                             u32x4 w; w.x = cvt_pk_bf16(v0[0], v0[1]); w.y = cvt_pk_bf16(v0[2], v0[3]); w.z = cvt_pk_bf16(v1[0], v1[1]); w.w = cvt_pk_bf16(v1[2], v1[3]);
;                             *(u32x4*)(P + (size_t)row * PROJ_LD + col0 + bj * 128) = w;
;                         }
;                     }
	s_nop 1
	v_mov_b32_e32 v4, v244
	v_fmamk_f32 v4, v4, 0x3a000000, v230
	v_mul_f32_e32 v5, 0x4b800000, v4
	v_cmp_gt_f32_e32 vcc, s94, v4
	s_nop 1
	v_cndmask_b32_e32 v4, v4, v5, vcc
	v_rsq_f32_e32 v4, v4
	v_add_u32_e32 v5, 0x80, v156
	v_mad_i64_i32 v[12:13], s[6:7], v5, s95, v[2:3]
	v_mul_f32_e32 v5, 0x45800000, v4
	v_cndmask_b32_e32 v4, v4, v5, vcc
	v_pk_mul_f32 v[6:7], v[86:87], v[4:5] op_sel_hi:[1,0]
	v_pk_mul_f32 v[8:9], v[84:85], v[4:5] op_sel_hi:[1,0]
	v_pk_mul_f32 v[10:11], v[82:83], v[4:5] op_sel_hi:[1,0]
	v_pk_mul_f32 v[14:15], v[80:81], v[4:5] op_sel_hi:[1,0]
	v_pk_mul_f32 v[16:17], v[78:79], v[4:5] op_sel_hi:[1,0]
	v_pk_mul_f32 v[18:19], v[76:77], v[4:5] op_sel_hi:[1,0]
	v_pk_mul_f32 v[20:21], v[74:75], v[4:5] op_sel_hi:[1,0]
	v_pk_mul_f32 v[22:23], v[72:73], v[4:5] op_sel_hi:[1,0]
	v_cvt_pk_bf16_f32 v4, v8, v9
	v_cvt_pk_bf16_f32 v5, v6, v7
	v_cvt_pk_bf16_f32 v6, v14, v15
	v_cvt_pk_bf16_f32 v7, v10, v11
	v_cvt_pk_bf16_f32 v8, v18, v19
	v_cvt_pk_bf16_f32 v9, v16, v17
	v_cvt_pk_bf16_f32 v10, v22, v23
	v_cvt_pk_bf16_f32 v11, v20, v21
	global_store_dwordx4 v[12:13], v[4:7], off
	global_store_dwordx4 v[12:13], v[8:11], off offset:256
	global_load_dword v248, v[0:1], off
	s_nop 1
	v_mov_b32_e32 v4, v245
	v_fmamk_f32 v4, v4, 0x3a000000, v230
	v_mul_f32_e32 v5, 0x4b800000, v4
	v_cmp_gt_f32_e32 vcc, s94, v4
	s_nop 1
	v_cndmask_b32_e32 v4, v4, v5, vcc
	v_rsq_f32_e32 v4, v4
	v_add_u32_e32 v5, 0x90, v156
	v_mad_i64_i32 v[12:13], s[6:7], v5, s95, v[2:3]
	v_mul_f32_e32 v5, 0x45800000, v4
	v_cndmask_b32_e32 v4, v4, v5, vcc
	v_pk_mul_f32 v[6:7], v[70:71], v[4:5] op_sel_hi:[1,0]
	v_pk_mul_f32 v[8:9], v[68:69], v[4:5] op_sel_hi:[1,0]
	v_pk_mul_f32 v[10:11], v[66:67], v[4:5] op_sel_hi:[1,0]
	v_pk_mul_f32 v[14:15], v[64:65], v[4:5] op_sel_hi:[1,0]
	v_pk_mul_f32 v[16:17], v[62:63], v[4:5] op_sel_hi:[1,0]
	v_pk_mul_f32 v[18:19], v[60:61], v[4:5] op_sel_hi:[1,0]
	v_pk_mul_f32 v[20:21], v[58:59], v[4:5] op_sel_hi:[1,0]
	v_pk_mul_f32 v[22:23], v[56:57], v[4:5] op_sel_hi:[1,0]
	v_cvt_pk_bf16_f32 v4, v8, v9
	v_cvt_pk_bf16_f32 v5, v6, v7
	v_cvt_pk_bf16_f32 v6, v14, v15
	v_cvt_pk_bf16_f32 v7, v10, v11
	v_cvt_pk_bf16_f32 v8, v18, v19
	v_cvt_pk_bf16_f32 v9, v16, v17
	v_cvt_pk_bf16_f32 v10, v22, v23
	v_cvt_pk_bf16_f32 v11, v20, v21
	global_store_dwordx4 v[12:13], v[4:7], off
	global_store_dwordx4 v[12:13], v[8:11], off offset:256
	global_load_dword v248, v[0:1], off
	s_nop 1
	v_mov_b32_e32 v4, v246
	v_fmamk_f32 v4, v4, 0x3a000000, v230
	v_mul_f32_e32 v5, 0x4b800000, v4
	v_cmp_gt_f32_e32 vcc, s94, v4
	s_nop 1
	v_cndmask_b32_e32 v4, v4, v5, vcc
	v_rsq_f32_e32 v4, v4
	v_add_u32_e32 v5, 0xa0, v156
	v_mad_i64_i32 v[12:13], s[6:7], v5, s95, v[2:3]
	v_mul_f32_e32 v5, 0x45800000, v4
	v_cndmask_b32_e32 v4, v4, v5, vcc
	v_pk_mul_f32 v[6:7], v[54:55], v[4:5] op_sel_hi:[1,0]
	v_pk_mul_f32 v[8:9], v[52:53], v[4:5] op_sel_hi:[1,0]
	v_pk_mul_f32 v[10:11], v[50:51], v[4:5] op_sel_hi:[1,0]
	v_pk_mul_f32 v[14:15], v[48:49], v[4:5] op_sel_hi:[1,0]
	v_pk_mul_f32 v[16:17], v[46:47], v[4:5] op_sel_hi:[1,0]
	v_pk_mul_f32 v[18:19], v[44:45], v[4:5] op_sel_hi:[1,0]
	v_pk_mul_f32 v[20:21], v[42:43], v[4:5] op_sel_hi:[1,0]
	v_pk_mul_f32 v[22:23], v[40:41], v[4:5] op_sel_hi:[1,0]
	v_cvt_pk_bf16_f32 v4, v8, v9
	v_cvt_pk_bf16_f32 v5, v6, v7
	v_cvt_pk_bf16_f32 v6, v14, v15
	v_cvt_pk_bf16_f32 v7, v10, v11
	v_cvt_pk_bf16_f32 v8, v18, v19
	v_cvt_pk_bf16_f32 v9, v16, v17
	v_cvt_pk_bf16_f32 v10, v22, v23
	v_cvt_pk_bf16_f32 v11, v20, v21
	global_store_dwordx4 v[12:13], v[4:7], off
	global_store_dwordx4 v[12:13], v[8:11], off offset:256
	global_load_dword v248, v[0:1], off
	s_nop 1
	v_mov_b32_e32 v0, v247
	v_fmamk_f32 v0, v0, 0x3a000000, v230
	v_mul_f32_e32 v1, 0x4b800000, v0
	v_cmp_gt_f32_e32 vcc, s94, v0
	s_nop 1
	v_cndmask_b32_e32 v0, v0, v1, vcc
	v_rsq_f32_e32 v0, v0
	v_add_u32_e32 v1, 0xb0, v156
	v_mad_i64_i32 v[8:9], s[6:7], v1, s95, v[2:3]
	v_mul_f32_e32 v1, 0x45800000, v0
	v_cndmask_b32_e32 v0, v0, v1, vcc
	v_pk_mul_f32 v[2:3], v[38:39], v[0:1] op_sel_hi:[1,0]
	v_pk_mul_f32 v[4:5], v[36:37], v[0:1] op_sel_hi:[1,0]
	v_pk_mul_f32 v[6:7], v[34:35], v[0:1] op_sel_hi:[1,0]
	v_pk_mul_f32 v[10:11], v[32:33], v[0:1] op_sel_hi:[1,0]
	v_pk_mul_f32 v[12:13], v[30:31], v[0:1] op_sel_hi:[1,0]
	v_pk_mul_f32 v[14:15], v[28:29], v[0:1] op_sel_hi:[1,0]
	v_pk_mul_f32 v[16:17], v[26:27], v[0:1] op_sel_hi:[1,0]
	v_pk_mul_f32 v[18:19], v[24:25], v[0:1] op_sel_hi:[1,0]
	v_cvt_pk_bf16_f32 v0, v4, v5
	v_cvt_pk_bf16_f32 v1, v2, v3
	v_cvt_pk_bf16_f32 v2, v10, v11
	v_cvt_pk_bf16_f32 v3, v6, v7
	v_cvt_pk_bf16_f32 v4, v14, v15
	v_cvt_pk_bf16_f32 v5, v12, v13
	v_cvt_pk_bf16_f32 v6, v18, v19
	v_cvt_pk_bf16_f32 v7, v16, v17
	global_store_dwordx4 v[8:9], v[0:3], off
	global_store_dwordx4 v[8:9], v[4:7], off offset:256
	s_mov_b64 s[6:7], 0
; __device__ __forceinline__ unsigned cvt_pk_bf16(float lo, float hi) { const f32x2 v = {lo, hi}; return __builtin_bit_cast(unsigned, __builtin_convertvector(v, bf16x2_t)); }
;     __device__ __forceinline__ void operator()(const f32x4 (&acc)[2][2][4][2], const Unit& u, int wr, int wc, int fr_, int fq_) const {
;     ...
;                 bf16_t* dst = (u.pn == 18) ? KSF : KWF;
; #pragma unroll
;                 for (int ai = 0; ai < 2; ++ai)
; #pragma unroll
;                     for (int m = 0; m < 4; ++m) {
;                         const int row = row0 + ai * 128 + m * 16; const int pos = row & (SEQ - 1), b = row >> 12;
;                         const float rs = rsqrtf(ssq[row] * (1.0f / DM) + 1e-6f);
; #pragma unroll
;                         for (int bj = 0; bj < 2; ++bj) {
;                             const f32x4 v0 = acc[ai][bj][m][0] * rs, v1 = acc[ai][bj][m][1] * rs;
;                             u32x4 w; w.x = cvt_pk_bf16(v0[0], v0[1]); w.y = cvt_pk_bf16(v0[2], v0[3]); w.z = cvt_pk_bf16(v1[0], v1[1]); w.w = cvt_pk_bf16(v1[2], v1[3]);
;                             const int ks = 2 * wc + (fq >> 1);
;                             *(u32x4*)(dst + (((((size_t)(b * 2 + bj) * 64 + (pos >> 6)) * 2 + ((pos >> 5) & 1)) * 8 + ks) * 64 + (fq & 1) * 32 + (pos & 31)) * 8) = w;
;                         }
.LBB0_739:
	s_andn2_b64 vcc, exec, s[6:7]
	s_cbranch_vccnz .LBB0_741
	v_ashrrev_i32_e32 v157, 31, v156
	v_lshl_add_u64 v[0:1], v[156:157], 2, s[18:19]
	global_load_dword v240, v[0:1], off
	global_load_dword v241, v[0:1], off offset:64
	global_load_dword v242, v[0:1], off offset:128
	global_load_dword v243, v[0:1], off offset:192
	global_load_dword v244, v[0:1], off offset:512
	global_load_dword v245, v[0:1], off offset:576
	global_load_dword v246, v[0:1], off offset:640
	global_load_dword v247, v[0:1], off offset:704
	v_ashrrev_i32_e32 v2, 1, v232
	v_ashrrev_i32_e32 v3, 11, v156
	v_add_u32_e32 v2, s85, v2
	v_and_b32_e32 v4, -2, v3
	v_or_b32_e32 v6, 1, v3
	v_ashrrev_i32_e32 v3, 31, v2
	v_lshlrev_b32_e32 v9, 5, v232
	v_lshlrev_b64 v[2:3], 6, v[2:3]
	v_and_or_b32 v154, v9, 32, v2
	v_lshlrev_b32_e32 v5, 4, v156
	s_cmp_eq_u32 s0, 18
	s_mov_b32 s1, 0x11715000
	v_and_b32_e32 v11, 0xfe00, v5
	v_ashrrev_i32_e32 v5, 31, v4
	v_and_b32_e32 v10, 31, v186
	s_cselect_b32 s1, s1, 0x11f15000
	v_lshlrev_b64 v[4:5], 16, v[4:5]
	s_add_u32 s6, s56, s1
	v_ashrrev_i32_e32 v7, 31, v6
	v_or_b32_e32 v4, v4, v11
	v_or_b32_e32 v2, v154, v10
	s_addc_u32 s7, s57, 0
	v_lshlrev_b64 v[6:7], 16, v[6:7]
	v_lshl_add_u64 v[4:5], v[4:5], 0, v[2:3]
	v_or_b32_e32 v6, v6, v11
	v_lshl_add_u64 v[12:13], v[4:5], 4, s[6:7]
	v_lshl_add_u64 v[6:7], v[6:7], 0, v[2:3]
	v_lshl_add_u64 v[14:15], v[6:7], 4, s[6:7]
	s_waitcnt vmcnt(0)
	v_mov_b32_e32 v8, v240
	v_fmamk_f32 v8, v8, 0x3a000000, v230
	v_mul_f32_e32 v9, 0x4b800000, v8
	v_cmp_gt_f32_e32 vcc, s94, v8
	s_nop 1
	v_cndmask_b32_e32 v8, v8, v9, vcc
	v_rsq_f32_e32 v8, v8
	s_nop 0
	v_mul_f32_e32 v4, 0x45800000, v8
	v_cndmask_b32_e32 v4, v8, v4, vcc
	v_pk_mul_f32 v[6:7], v[150:151], v[4:5] op_sel_hi:[1,0]
	v_pk_mul_f32 v[8:9], v[148:149], v[4:5] op_sel_hi:[1,0]
	v_pk_mul_f32 v[10:11], v[146:147], v[4:5] op_sel_hi:[1,0]
	v_pk_mul_f32 v[16:17], v[144:145], v[4:5] op_sel_hi:[1,0]
	v_pk_mul_f32 v[18:19], v[142:143], v[4:5] op_sel_hi:[1,0]
	v_pk_mul_f32 v[20:21], v[140:141], v[4:5] op_sel_hi:[1,0]
	v_pk_mul_f32 v[22:23], v[138:139], v[4:5] op_sel_hi:[1,0]
	v_pk_mul_f32 v[152:153], v[136:137], v[4:5] op_sel_hi:[1,0]
	v_cvt_pk_bf16_f32 v4, v8, v9
	v_cvt_pk_bf16_f32 v5, v6, v7
	v_cvt_pk_bf16_f32 v6, v16, v17
	v_cvt_pk_bf16_f32 v7, v10, v11
	v_cvt_pk_bf16_f32 v8, v20, v21
	v_cvt_pk_bf16_f32 v9, v18, v19
	v_cvt_pk_bf16_f32 v10, v152, v153
	v_cvt_pk_bf16_f32 v11, v22, v23
	global_store_dwordx4 v[12:13], v[4:7], off
	global_store_dwordx4 v[14:15], v[8:11], off
	global_load_dword v248, v[0:1], off
	v_add_u32_e32 v5, 16, v156
	v_ashrrev_i32_e32 v7, 11, v5
	v_and_b32_e32 v6, -2, v7
	v_or_b32_e32 v8, 1, v7
	v_lshlrev_b32_e32 v5, 4, v5
	v_ashrrev_i32_e32 v7, 31, v6
	v_ashrrev_i32_e32 v9, 31, v8
	v_and_b32_e32 v11, 0xfe00, v5
	v_lshlrev_b64 v[6:7], 16, v[6:7]
	v_lshlrev_b64 v[8:9], 16, v[8:9]
	v_or_b32_e32 v6, v6, v11
	v_or_b32_e32 v8, v8, v11
	v_bitop3_b32 v4, v186, 16, 31 bitop3:0x6c
	v_mov_b32_e32 v5, v3
	v_or_b32_e32 v4, v154, v4
	v_lshl_add_u64 v[6:7], v[6:7], 0, v[4:5]
	v_lshl_add_u64 v[14:15], v[6:7], 4, s[6:7]
	v_lshl_add_u64 v[8:9], v[8:9], 0, v[4:5]
	v_lshl_add_u64 v[16:17], v[8:9], 4, s[6:7]
	s_nop 1
	v_mov_b32_e32 v10, v241
	v_fmamk_f32 v10, v10, 0x3a000000, v230
	v_mul_f32_e32 v11, 0x4b800000, v10
	v_cmp_gt_f32_e32 vcc, s94, v10
	s_nop 1
	v_cndmask_b32_e32 v10, v10, v11, vcc
	v_rsq_f32_e32 v10, v10
	s_nop 0
	v_mul_f32_e32 v6, 0x45800000, v10
	v_cndmask_b32_e32 v6, v10, v6, vcc
	v_pk_mul_f32 v[8:9], v[134:135], v[6:7] op_sel_hi:[1,0]
	v_pk_mul_f32 v[10:11], v[132:133], v[6:7] op_sel_hi:[1,0]
	v_pk_mul_f32 v[12:13], v[130:131], v[6:7] op_sel_hi:[1,0]
	v_pk_mul_f32 v[18:19], v[128:129], v[6:7] op_sel_hi:[1,0]
	v_pk_mul_f32 v[20:21], v[126:127], v[6:7] op_sel_hi:[1,0]
	v_pk_mul_f32 v[22:23], v[124:125], v[6:7] op_sel_hi:[1,0]
	v_pk_mul_f32 v[152:153], v[122:123], v[6:7] op_sel_hi:[1,0]
	v_pk_mul_f32 v[154:155], v[120:121], v[6:7] op_sel_hi:[1,0]
	v_cvt_pk_bf16_f32 v6, v10, v11
	v_cvt_pk_bf16_f32 v7, v8, v9
	v_cvt_pk_bf16_f32 v8, v18, v19
	v_cvt_pk_bf16_f32 v9, v12, v13
	v_cvt_pk_bf16_f32 v10, v22, v23
	v_cvt_pk_bf16_f32 v11, v20, v21
	v_cvt_pk_bf16_f32 v12, v154, v155
	v_cvt_pk_bf16_f32 v13, v152, v153
	global_store_dwordx4 v[14:15], v[6:9], off
	global_store_dwordx4 v[16:17], v[10:13], off
	global_load_dword v248, v[0:1], off
	v_add_u32_e32 v6, 32, v156
	v_ashrrev_i32_e32 v7, 11, v6
	v_lshlrev_b32_e32 v8, 4, v6
	v_and_b32_e32 v6, -2, v7
	v_and_b32_e32 v11, 0xfe00, v8
	v_or_b32_e32 v8, 1, v7
	v_ashrrev_i32_e32 v7, 31, v6
	v_ashrrev_i32_e32 v9, 31, v8
	v_lshlrev_b64 v[6:7], 16, v[6:7]
	v_lshlrev_b64 v[8:9], 16, v[8:9]
	v_or_b32_e32 v6, v6, v11
	v_or_b32_e32 v8, v8, v11
	v_lshl_add_u64 v[6:7], v[6:7], 0, v[2:3]
	v_lshl_add_u64 v[14:15], v[6:7], 4, s[6:7]
	v_lshl_add_u64 v[8:9], v[8:9], 0, v[2:3]
	v_lshl_add_u64 v[16:17], v[8:9], 4, s[6:7]
	s_nop 1
	v_mov_b32_e32 v10, v242
	v_fmamk_f32 v10, v10, 0x3a000000, v230
	v_mul_f32_e32 v11, 0x4b800000, v10
	v_cmp_gt_f32_e32 vcc, s94, v10
	s_nop 1
	v_cndmask_b32_e32 v10, v10, v11, vcc
	v_rsq_f32_e32 v10, v10
	s_nop 0
	v_mul_f32_e32 v6, 0x45800000, v10
	v_cndmask_b32_e32 v6, v10, v6, vcc
	v_pk_mul_f32 v[8:9], v[118:119], v[6:7] op_sel_hi:[1,0]
	v_pk_mul_f32 v[10:11], v[116:117], v[6:7] op_sel_hi:[1,0]
	v_pk_mul_f32 v[12:13], v[114:115], v[6:7] op_sel_hi:[1,0]
	v_pk_mul_f32 v[18:19], v[112:113], v[6:7] op_sel_hi:[1,0]
	v_pk_mul_f32 v[20:21], v[110:111], v[6:7] op_sel_hi:[1,0]
	v_pk_mul_f32 v[22:23], v[108:109], v[6:7] op_sel_hi:[1,0]
	v_pk_mul_f32 v[152:153], v[106:107], v[6:7] op_sel_hi:[1,0]
	v_pk_mul_f32 v[154:155], v[104:105], v[6:7] op_sel_hi:[1,0]
	v_cvt_pk_bf16_f32 v6, v10, v11
	v_cvt_pk_bf16_f32 v7, v8, v9
; __device__ __forceinline__ unsigned cvt_pk_bf16(float lo, float hi) { const f32x2 v = {lo, hi}; return __builtin_bit_cast(unsigned, __builtin_convertvector(v, bf16x2_t)); }
;     __device__ __forceinline__ void operator()(const f32x4 (&acc)[2][2][4][2], const Unit& u, int wr, int wc, int fr_, int fq_) const {
;     ...
;                     for (int m = 0; m < 4; ++m) {
;                         const int row = row0 + ai * 128 + m * 16; const int pos = row & (SEQ - 1), b = row >> 12;
;                         const float rs = rsqrtf(ssq[row] * (1.0f / DM) + 1e-6f);
; #pragma unroll
;                         for (int bj = 0; bj < 2; ++bj) {
;                             const f32x4 v0 = acc[ai][bj][m][0] * rs, v1 = acc[ai][bj][m][1] * rs;
;                             u32x4 w; w.x = cvt_pk_bf16(v0[0], v0[1]); w.y = cvt_pk_bf16(v0[2], v0[3]); w.z = cvt_pk_bf16(v1[0], v1[1]); w.w = cvt_pk_bf16(v1[2], v1[3]);
;                             const int ks = 2 * wc + (fq >> 1);
;                             *(u32x4*)(dst + (((((size_t)(b * 2 + bj) * 64 + (pos >> 6)) * 2 + ((pos >> 5) & 1)) * 8 + ks) * 64 + (fq & 1) * 32 + (pos & 31)) * 8) = w;
;                         }
	v_cvt_pk_bf16_f32 v8, v18, v19
	v_cvt_pk_bf16_f32 v9, v12, v13
	v_cvt_pk_bf16_f32 v10, v22, v23
	v_cvt_pk_bf16_f32 v11, v20, v21
	v_cvt_pk_bf16_f32 v12, v154, v155
	v_cvt_pk_bf16_f32 v13, v152, v153
	global_store_dwordx4 v[14:15], v[6:9], off
	global_store_dwordx4 v[16:17], v[10:13], off
	global_load_dword v248, v[0:1], off
	v_add_u32_e32 v6, 48, v156
	v_ashrrev_i32_e32 v7, 11, v6
	v_lshlrev_b32_e32 v8, 4, v6
	v_and_b32_e32 v6, -2, v7
	v_and_b32_e32 v11, 0xfe00, v8
	v_or_b32_e32 v8, 1, v7
	v_ashrrev_i32_e32 v7, 31, v6
	v_ashrrev_i32_e32 v9, 31, v8
	v_lshlrev_b64 v[6:7], 16, v[6:7]
	v_lshlrev_b64 v[8:9], 16, v[8:9]
	v_or_b32_e32 v6, v6, v11
	v_or_b32_e32 v8, v8, v11
	v_lshl_add_u64 v[6:7], v[6:7], 0, v[4:5]
	v_lshl_add_u64 v[14:15], v[6:7], 4, s[6:7]
	v_lshl_add_u64 v[8:9], v[8:9], 0, v[4:5]
	v_lshl_add_u64 v[16:17], v[8:9], 4, s[6:7]
	s_nop 1
	v_mov_b32_e32 v10, v243
	v_fmamk_f32 v10, v10, 0x3a000000, v230
	v_mul_f32_e32 v11, 0x4b800000, v10
	v_cmp_gt_f32_e32 vcc, s94, v10
	s_nop 1
	v_cndmask_b32_e32 v10, v10, v11, vcc
	v_rsq_f32_e32 v10, v10
	s_nop 0
	v_mul_f32_e32 v6, 0x45800000, v10
	v_cndmask_b32_e32 v6, v10, v6, vcc
	v_pk_mul_f32 v[8:9], v[102:103], v[6:7] op_sel_hi:[1,0]
	v_pk_mul_f32 v[10:11], v[100:101], v[6:7] op_sel_hi:[1,0]
	v_pk_mul_f32 v[12:13], v[98:99], v[6:7] op_sel_hi:[1,0]
	v_pk_mul_f32 v[18:19], v[96:97], v[6:7] op_sel_hi:[1,0]
	v_pk_mul_f32 v[20:21], v[94:95], v[6:7] op_sel_hi:[1,0]
	v_pk_mul_f32 v[22:23], v[92:93], v[6:7] op_sel_hi:[1,0]
	v_pk_mul_f32 v[152:153], v[90:91], v[6:7] op_sel_hi:[1,0]
	v_pk_mul_f32 v[154:155], v[88:89], v[6:7] op_sel_hi:[1,0]
	v_cvt_pk_bf16_f32 v6, v10, v11
	v_cvt_pk_bf16_f32 v7, v8, v9
	v_cvt_pk_bf16_f32 v8, v18, v19
	v_cvt_pk_bf16_f32 v9, v12, v13
	v_cvt_pk_bf16_f32 v10, v22, v23
	v_cvt_pk_bf16_f32 v11, v20, v21
	v_cvt_pk_bf16_f32 v12, v154, v155
	v_cvt_pk_bf16_f32 v13, v152, v153
	global_store_dwordx4 v[14:15], v[6:9], off
	global_store_dwordx4 v[16:17], v[10:13], off
	global_load_dword v248, v[0:1], off
	v_add_u32_e32 v6, 0x80, v156
	v_ashrrev_i32_e32 v7, 11, v6
	v_lshlrev_b32_e32 v8, 4, v6
	v_and_b32_e32 v6, -2, v7
	v_and_b32_e32 v11, 0xfe00, v8
	v_or_b32_e32 v8, 1, v7
	v_ashrrev_i32_e32 v7, 31, v6
	v_ashrrev_i32_e32 v9, 31, v8
	v_lshlrev_b64 v[6:7], 16, v[6:7]
	v_lshlrev_b64 v[8:9], 16, v[8:9]
	v_or_b32_e32 v6, v6, v11
	v_or_b32_e32 v8, v8, v11
	v_lshl_add_u64 v[6:7], v[6:7], 0, v[2:3]
	v_lshl_add_u64 v[14:15], v[6:7], 4, s[6:7]
	v_lshl_add_u64 v[8:9], v[8:9], 0, v[2:3]
	v_lshl_add_u64 v[16:17], v[8:9], 4, s[6:7]
	s_nop 1
	v_mov_b32_e32 v10, v244
	v_fmamk_f32 v10, v10, 0x3a000000, v230
	v_mul_f32_e32 v11, 0x4b800000, v10
	v_cmp_gt_f32_e32 vcc, s94, v10
	s_nop 1
	v_cndmask_b32_e32 v10, v10, v11, vcc
	v_rsq_f32_e32 v10, v10
	s_nop 0
	v_mul_f32_e32 v6, 0x45800000, v10
	v_cndmask_b32_e32 v6, v10, v6, vcc
	v_pk_mul_f32 v[8:9], v[86:87], v[6:7] op_sel_hi:[1,0]
	v_pk_mul_f32 v[10:11], v[84:85], v[6:7] op_sel_hi:[1,0]
	v_pk_mul_f32 v[12:13], v[82:83], v[6:7] op_sel_hi:[1,0]
	v_pk_mul_f32 v[18:19], v[80:81], v[6:7] op_sel_hi:[1,0]
	v_pk_mul_f32 v[20:21], v[78:79], v[6:7] op_sel_hi:[1,0]
	v_pk_mul_f32 v[22:23], v[76:77], v[6:7] op_sel_hi:[1,0]
	v_pk_mul_f32 v[152:153], v[74:75], v[6:7] op_sel_hi:[1,0]
	v_pk_mul_f32 v[154:155], v[72:73], v[6:7] op_sel_hi:[1,0]
	v_cvt_pk_bf16_f32 v6, v10, v11
	v_cvt_pk_bf16_f32 v7, v8, v9
	v_cvt_pk_bf16_f32 v8, v18, v19
	v_cvt_pk_bf16_f32 v9, v12, v13
	v_cvt_pk_bf16_f32 v10, v22, v23
	v_cvt_pk_bf16_f32 v11, v20, v21
	v_cvt_pk_bf16_f32 v12, v154, v155
	v_cvt_pk_bf16_f32 v13, v152, v153
	global_store_dwordx4 v[14:15], v[6:9], off
	global_store_dwordx4 v[16:17], v[10:13], off
	global_load_dword v248, v[0:1], off
	v_add_u32_e32 v6, 0x90, v156
	v_ashrrev_i32_e32 v7, 11, v6
	v_lshlrev_b32_e32 v8, 4, v6
	v_and_b32_e32 v6, -2, v7
	v_and_b32_e32 v11, 0xfe00, v8
	v_or_b32_e32 v8, 1, v7
	v_ashrrev_i32_e32 v7, 31, v6
	v_ashrrev_i32_e32 v9, 31, v8
	v_lshlrev_b64 v[6:7], 16, v[6:7]
	v_lshlrev_b64 v[8:9], 16, v[8:9]
	v_or_b32_e32 v6, v6, v11
	v_or_b32_e32 v8, v8, v11
	v_lshl_add_u64 v[6:7], v[6:7], 0, v[4:5]
	v_lshl_add_u64 v[14:15], v[6:7], 4, s[6:7]
	v_lshl_add_u64 v[8:9], v[8:9], 0, v[4:5]
	v_lshl_add_u64 v[16:17], v[8:9], 4, s[6:7]
	s_nop 1
	v_mov_b32_e32 v10, v245
	v_fmamk_f32 v10, v10, 0x3a000000, v230
	v_mul_f32_e32 v11, 0x4b800000, v10
; __device__ __forceinline__ unsigned cvt_pk_bf16(float lo, float hi) { const f32x2 v = {lo, hi}; return __builtin_bit_cast(unsigned, __builtin_convertvector(v, bf16x2_t)); }
;     __device__ __forceinline__ void operator()(const f32x4 (&acc)[2][2][4][2], const Unit& u, int wr, int wc, int fr_, int fq_) const {
;     ...
;                     for (int m = 0; m < 4; ++m) {
;                         const int row = row0 + ai * 128 + m * 16; const int pos = row & (SEQ - 1), b = row >> 12;
;                         const float rs = rsqrtf(ssq[row] * (1.0f / DM) + 1e-6f);
; #pragma unroll
;                         for (int bj = 0; bj < 2; ++bj) {
;                             const f32x4 v0 = acc[ai][bj][m][0] * rs, v1 = acc[ai][bj][m][1] * rs;
;                             u32x4 w; w.x = cvt_pk_bf16(v0[0], v0[1]); w.y = cvt_pk_bf16(v0[2], v0[3]); w.z = cvt_pk_bf16(v1[0], v1[1]); w.w = cvt_pk_bf16(v1[2], v1[3]);
;                             const int ks = 2 * wc + (fq >> 1);
;                             *(u32x4*)(dst + (((((size_t)(b * 2 + bj) * 64 + (pos >> 6)) * 2 + ((pos >> 5) & 1)) * 8 + ks) * 64 + (fq & 1) * 32 + (pos & 31)) * 8) = w;
;                         }
	v_cmp_gt_f32_e32 vcc, s94, v10
	s_nop 1
	v_cndmask_b32_e32 v10, v10, v11, vcc
	v_rsq_f32_e32 v10, v10
	s_nop 0
	v_mul_f32_e32 v6, 0x45800000, v10
	v_cndmask_b32_e32 v6, v10, v6, vcc
	v_pk_mul_f32 v[8:9], v[70:71], v[6:7] op_sel_hi:[1,0]
	v_pk_mul_f32 v[10:11], v[68:69], v[6:7] op_sel_hi:[1,0]
	v_pk_mul_f32 v[12:13], v[66:67], v[6:7] op_sel_hi:[1,0]
	v_pk_mul_f32 v[18:19], v[64:65], v[6:7] op_sel_hi:[1,0]
	v_pk_mul_f32 v[20:21], v[62:63], v[6:7] op_sel_hi:[1,0]
	v_pk_mul_f32 v[22:23], v[60:61], v[6:7] op_sel_hi:[1,0]
	v_pk_mul_f32 v[152:153], v[58:59], v[6:7] op_sel_hi:[1,0]
	v_pk_mul_f32 v[154:155], v[56:57], v[6:7] op_sel_hi:[1,0]
	v_cvt_pk_bf16_f32 v6, v10, v11
	v_cvt_pk_bf16_f32 v7, v8, v9
	v_cvt_pk_bf16_f32 v8, v18, v19
	v_cvt_pk_bf16_f32 v9, v12, v13
	v_cvt_pk_bf16_f32 v10, v22, v23
	v_cvt_pk_bf16_f32 v11, v20, v21
	v_cvt_pk_bf16_f32 v12, v154, v155
	v_cvt_pk_bf16_f32 v13, v152, v153
	global_store_dwordx4 v[14:15], v[6:9], off
	global_store_dwordx4 v[16:17], v[10:13], off
	global_load_dword v248, v[0:1], off
	v_add_u32_e32 v6, 0xa0, v156
	v_ashrrev_i32_e32 v7, 11, v6
	v_lshlrev_b32_e32 v8, 4, v6
	v_and_b32_e32 v6, -2, v7
	v_and_b32_e32 v11, 0xfe00, v8
	v_or_b32_e32 v8, 1, v7
	v_ashrrev_i32_e32 v7, 31, v6
	v_ashrrev_i32_e32 v9, 31, v8
	v_lshlrev_b64 v[6:7], 16, v[6:7]
	v_lshlrev_b64 v[8:9], 16, v[8:9]
	v_or_b32_e32 v6, v6, v11
	v_or_b32_e32 v8, v8, v11
	v_lshl_add_u64 v[6:7], v[6:7], 0, v[2:3]
	v_lshl_add_u64 v[14:15], v[6:7], 4, s[6:7]
	v_lshl_add_u64 v[2:3], v[8:9], 0, v[2:3]
	v_lshl_add_u64 v[2:3], v[2:3], 4, s[6:7]
	s_nop 1
	v_mov_b32_e32 v10, v246
	v_fmamk_f32 v10, v10, 0x3a000000, v230
	v_mul_f32_e32 v11, 0x4b800000, v10
	v_cmp_gt_f32_e32 vcc, s94, v10
	s_nop 1
	v_cndmask_b32_e32 v10, v10, v11, vcc
	v_rsq_f32_e32 v10, v10
	s_nop 0
	v_mul_f32_e32 v6, 0x45800000, v10
	v_cndmask_b32_e32 v6, v10, v6, vcc
	v_pk_mul_f32 v[8:9], v[54:55], v[6:7] op_sel_hi:[1,0]
	v_pk_mul_f32 v[10:11], v[52:53], v[6:7] op_sel_hi:[1,0]
	v_pk_mul_f32 v[12:13], v[50:51], v[6:7] op_sel_hi:[1,0]
	v_pk_mul_f32 v[16:17], v[48:49], v[6:7] op_sel_hi:[1,0]
	v_pk_mul_f32 v[18:19], v[46:47], v[6:7] op_sel_hi:[1,0]
	v_pk_mul_f32 v[20:21], v[44:45], v[6:7] op_sel_hi:[1,0]
	v_pk_mul_f32 v[22:23], v[42:43], v[6:7] op_sel_hi:[1,0]
	v_pk_mul_f32 v[152:153], v[40:41], v[6:7] op_sel_hi:[1,0]
	v_cvt_pk_bf16_f32 v6, v10, v11
	v_cvt_pk_bf16_f32 v7, v8, v9
	v_cvt_pk_bf16_f32 v8, v16, v17
	v_cvt_pk_bf16_f32 v9, v12, v13
	v_cvt_pk_bf16_f32 v10, v20, v21
	v_cvt_pk_bf16_f32 v11, v18, v19
	v_cvt_pk_bf16_f32 v12, v152, v153
	v_cvt_pk_bf16_f32 v13, v22, v23
	global_store_dwordx4 v[14:15], v[6:9], off
	global_store_dwordx4 v[2:3], v[10:13], off
	global_load_dword v248, v[0:1], off
	v_add_u32_e32 v0, 0xb0, v156
	v_ashrrev_i32_e32 v1, 11, v0
	v_lshlrev_b32_e32 v2, 4, v0
	v_and_b32_e32 v0, -2, v1
	v_and_b32_e32 v7, 0xfe00, v2
	v_or_b32_e32 v2, 1, v1
	v_ashrrev_i32_e32 v1, 31, v0
	v_ashrrev_i32_e32 v3, 31, v2
	v_lshlrev_b64 v[0:1], 16, v[0:1]
	v_lshlrev_b64 v[2:3], 16, v[2:3]
	v_or_b32_e32 v0, v0, v7
	v_or_b32_e32 v2, v2, v7
	v_lshl_add_u64 v[0:1], v[0:1], 0, v[4:5]
	v_lshl_add_u64 v[8:9], v[0:1], 4, s[6:7]
	v_lshl_add_u64 v[2:3], v[2:3], 0, v[4:5]
	v_lshl_add_u64 v[10:11], v[2:3], 4, s[6:7]
	s_nop 1
	v_mov_b32_e32 v6, v247
	v_fmamk_f32 v6, v6, 0x3a000000, v230
	v_mul_f32_e32 v7, 0x4b800000, v6
	v_cmp_gt_f32_e32 vcc, s94, v6
	s_nop 1
	v_cndmask_b32_e32 v6, v6, v7, vcc
	v_rsq_f32_e32 v6, v6
	s_nop 0
	v_mul_f32_e32 v0, 0x45800000, v6
	v_cndmask_b32_e32 v0, v6, v0, vcc
	v_pk_mul_f32 v[2:3], v[38:39], v[0:1] op_sel_hi:[1,0]
	v_pk_mul_f32 v[4:5], v[36:37], v[0:1] op_sel_hi:[1,0]
	v_pk_mul_f32 v[6:7], v[34:35], v[0:1] op_sel_hi:[1,0]
	v_pk_mul_f32 v[12:13], v[32:33], v[0:1] op_sel_hi:[1,0]
	v_pk_mul_f32 v[14:15], v[30:31], v[0:1] op_sel_hi:[1,0]
	v_pk_mul_f32 v[16:17], v[28:29], v[0:1] op_sel_hi:[1,0]
	v_pk_mul_f32 v[18:19], v[26:27], v[0:1] op_sel_hi:[1,0]
	v_pk_mul_f32 v[20:21], v[24:25], v[0:1] op_sel_hi:[1,0]
	v_cvt_pk_bf16_f32 v0, v4, v5
	v_cvt_pk_bf16_f32 v1, v2, v3
	v_cvt_pk_bf16_f32 v2, v12, v13
	v_cvt_pk_bf16_f32 v3, v6, v7
	v_cvt_pk_bf16_f32 v4, v16, v17
	v_cvt_pk_bf16_f32 v5, v14, v15
	v_cvt_pk_bf16_f32 v6, v20, v21
	v_cvt_pk_bf16_f32 v7, v18, v19
	global_store_dwordx4 v[8:9], v[0:3], off
	global_store_dwordx4 v[10:11], v[4:7], off
